# counted lgkmcnt waits in the four wide GEMM K loops: each MFMA waits only for its own ds_read_b128 fragments
# speedup vs baseline: 1.0075x; 1.0007x over previous
; #define MFMA(a, b, c) __builtin_amdgcn_mfma_f32_32x32x16_bf16((a), (b), (c), 0, 0, 0)
; template <int K, typename Epi>
; DI void gemm_tile_wide(const u16* __restrict__ A, int lda, const u16* __restrict__ Bt, int ldb, int m0, int n0, char* smem, Epi epi) {
;     ...
;   auto issue = [&](int slice, int st) {
; #pragma unroll
;     for (int i = 0; i < 4; ++i) {
;       if (i < 2) __builtin_amdgcn_global_load_lds((const unsigned*)(ap[i] + slice * 32), (unsigned*)(ldst + st + i * 4096), 16, 0, 0);
;       __builtin_amdgcn_global_load_lds((const unsigned*)(bp[i] + slice * 32), (unsigned*)(ldst + st + AB + i * 4096), 16, 0, 0);
;     }
;   };
;   __syncthreads();
;   issue(0, 0);
;   for (int kt = 0; kt < NS; ++kt) {
;     asm volatile("s_waitcnt vmcnt(0)" ::: "memory");
;     __syncthreads();
;     const int cur = (kt & 1) * STB;
;     if (kt + 1 < NS) issue(kt + 1, STB - cur);
;     const char* Sg = smem + cur;
;     bf16x8 a[2][2], b[2][4];
; #pragma unroll
;     for (int kk = 0; kk < 2; ++kk) {
; #pragma unroll
;       for (int i = 0; i < 2; ++i) a[kk][i] = *(const bf16x8*)(Sg + aoff[i][kk]);
; #pragma unroll
;       for (int j = 0; j < 4; ++j) b[kk][j] = *(const bf16x8*)(Sg + boff[j][kk]);
;     }
;     __builtin_amdgcn_sched_barrier(0);
;     __builtin_amdgcn_s_setprio(1);
; #pragma unroll
;     for (int kk = 0; kk < 2; ++kk)
; #pragma unroll
;       for (int i = 0; i < 2; ++i)
; #pragma unroll
;         for (int j = 0; j < 4; ++j) acc[i][j] = MFMA(a[kk][i], b[kk][j], acc[i][j]);
;     __builtin_amdgcn_s_setprio(0);
;   }
;   float* Cs = (float*)smem;
; #pragma unroll
;   for (int half = 0; half < 2; ++half) {
;     __syncthreads();
;     if (wn == half) {
.LBB0_142:
	s_bitcmp1_b32 s2, 0
	s_cselect_b32 s3, 0x6000, 0
	v_subrev_u32_e32 v156, s3, v147
	v_add_u32_e32 v157, 0x6000, v156
	v_lshl_add_u64 v[154:155], v[128:129], 0, s[0:1]
	v_readfirstlane_b32 s4, v157
	v_add_u32_e32 v157, 0x8000, v156
	s_mov_b32 m0, s4
	v_readfirstlane_b32 s4, v157
	v_add_u32_e32 v157, 0x7000, v156
	s_waitcnt vmcnt(0)
	s_waitcnt vmcnt(0) lgkmcnt(0)
	s_barrier
	global_load_lds_dwordx4 v[154:155], off
	v_lshl_add_u64 v[154:155], v[130:131], 0, s[100:101]
	s_mov_b32 m0, s4
	v_readfirstlane_b32 s4, v157
	v_add_u32_e32 v157, 0x9000, v156
	global_load_lds_dwordx4 v[154:155], off
	v_lshl_add_u64 v[154:155], v[132:133], 0, s[0:1]
	s_mov_b32 m0, s4
	v_readfirstlane_b32 s4, v157
	v_add_u32_e32 v157, 0xa000, v156
	global_load_lds_dwordx4 v[154:155], off
	v_lshl_add_u64 v[154:155], v[134:135], 0, s[100:101]
	s_mov_b32 m0, s4
	v_readfirstlane_b32 s4, v157
	v_add_u32_e32 v156, 0xb000, v156
	global_load_lds_dwordx4 v[154:155], off
	v_lshl_add_u64 v[154:155], v[138:139], 0, s[100:101]
	s_mov_b32 m0, s4
	v_readfirstlane_b32 s4, v156
	global_load_lds_dwordx4 v[154:155], off
	v_lshl_add_u64 v[154:155], v[140:141], 0, s[100:101]
	s_mov_b32 m0, s4
	v_add_u32_e32 v158, s3, v145
	global_load_lds_dwordx4 v[154:155], off
	v_add_u32_e32 v162, s3, v148
	ds_read_b128 v[154:157], v158
	ds_read_b128 v[158:161], v158 offset:2048
	ds_read_b128 v[168:171], v162 offset:8192
	v_add_u32_e32 v162, s3, v149
	ds_read_b128 v[172:175], v162 offset:2048
	ds_read_b128 v[176:179], v162 offset:4096
	ds_read_b128 v[180:183], v162 offset:6144
	v_add_u32_e32 v162, s3, v146
	ds_read_b128 v[188:191], v162
	ds_read_b128 v[192:195], v162 offset:2048
	v_add_u32_e32 v162, s3, v150
	ds_read_b128 v[196:199], v162 offset:8192
	v_add_u32_e32 v162, s3, v151
	ds_read_b128 v[200:203], v162 offset:8192
	v_add_u32_e32 v162, s3, v152
	ds_read_b128 v[204:207], v162 offset:8192
	v_add_u32_e32 v162, s3, v153
	ds_read_b128 v[208:211], v162 offset:8192
	s_add_i32 s2, s2, 1
	s_setprio 1
	s_waitcnt lgkmcnt(9)
	v_mfma_f32_32x32x16_bf16 v[0:15], v[154:157], v[168:171], v[0:15]
	s_waitcnt lgkmcnt(8)
	v_mfma_f32_32x32x16_bf16 v[48:63], v[154:157], v[172:175], v[48:63]
	s_waitcnt lgkmcnt(7)
	v_mfma_f32_32x32x16_bf16 v[16:31], v[154:157], v[176:179], v[16:31]
	s_waitcnt lgkmcnt(6)
	v_mfma_f32_32x32x16_bf16 v[64:79], v[154:157], v[180:183], v[64:79]
	v_mfma_f32_32x32x16_bf16 v[32:47], v[158:161], v[168:171], v[32:47]
	v_mfma_f32_32x32x16_bf16 v[96:111], v[158:161], v[172:175], v[96:111]
	v_mfma_f32_32x32x16_bf16 v[80:95], v[158:161], v[176:179], v[80:95]
	v_mfma_f32_32x32x16_bf16 v[112:127], v[158:161], v[180:183], v[112:127]
	s_waitcnt lgkmcnt(3)
	v_mfma_f32_32x32x16_bf16 v[0:15], v[188:191], v[196:199], v[0:15]
	s_waitcnt lgkmcnt(2)
	v_mfma_f32_32x32x16_bf16 v[48:63], v[188:191], v[200:203], v[48:63]
	s_waitcnt lgkmcnt(1)
	v_mfma_f32_32x32x16_bf16 v[16:31], v[188:191], v[204:207], v[16:31]
	s_waitcnt lgkmcnt(0)
	v_mfma_f32_32x32x16_bf16 v[64:79], v[188:191], v[208:211], v[64:79]
	v_mfma_f32_32x32x16_bf16 v[32:47], v[192:195], v[196:199], v[32:47]
	v_mfma_f32_32x32x16_bf16 v[96:111], v[192:195], v[200:203], v[96:111]
	v_mfma_f32_32x32x16_bf16 v[80:95], v[192:195], v[204:207], v[80:95]
	v_mfma_f32_32x32x16_bf16 v[112:127], v[192:195], v[208:211], v[112:127]
	s_setprio 0
	s_add_u32 s0, s0, 64
	s_addc_u32 s1, s1, 0
	s_add_u32 s100, s100, 0x30000
	s_addc_u32 s101, s101, 0
	s_cmpk_eq_i32 s0, 0x7c0
	s_cbranch_scc0 .LBB0_142
	s_waitcnt vmcnt(0)
	s_waitcnt vmcnt(0)
	s_barrier
	ds_read_b128 v[128:131], v153 offset:32768
	ds_read_b128 v[132:135], v152 offset:32768
	ds_read_b128 v[138:141], v151 offset:32768
	ds_read_b128 v[150:153], v150 offset:32768
	ds_read_b128 v[154:157], v146 offset:26624
	ds_read_b128 v[158:161], v146 offset:24576
	ds_read_b128 v[168:171], v149 offset:30720
	ds_read_b128 v[172:175], v149 offset:28672
	ds_read_b128 v[176:179], v149 offset:26624
	ds_read_b128 v[146:149], v148 offset:32768
	ds_read_b128 v[180:183], v145 offset:26624
	ds_read_b128 v[188:191], v145 offset:24576
	s_setprio 1
	s_waitcnt lgkmcnt(0)
	v_mfma_f32_32x32x16_bf16 v[0:15], v[188:191], v[146:149], v[0:15]
	v_mfma_f32_32x32x16_bf16 v[48:63], v[188:191], v[176:179], v[48:63]
	v_mfma_f32_32x32x16_bf16 v[16:31], v[188:191], v[172:175], v[16:31]
	v_mfma_f32_32x32x16_bf16 v[64:79], v[188:191], v[168:171], v[64:79]
	v_mfma_f32_32x32x16_bf16 v[32:47], v[180:183], v[146:149], v[32:47]
	v_mfma_f32_32x32x16_bf16 v[96:111], v[180:183], v[176:179], v[96:111]
	v_mfma_f32_32x32x16_bf16 v[80:95], v[180:183], v[172:175], v[80:95]
	v_mfma_f32_32x32x16_bf16 v[112:127], v[180:183], v[168:171], v[112:127]
	v_mfma_f32_32x32x16_bf16 v[0:15], v[158:161], v[150:153], v[0:15]
	v_mfma_f32_32x32x16_bf16 v[48:63], v[158:161], v[138:141], v[48:63]
	v_mfma_f32_32x32x16_bf16 v[16:31], v[158:161], v[132:135], v[16:31]
	v_mfma_f32_32x32x16_bf16 v[64:79], v[158:161], v[128:131], v[64:79]
	v_mfma_f32_32x32x16_bf16 v[32:47], v[154:157], v[150:153], v[32:47]
	v_mfma_f32_32x32x16_bf16 v[96:111], v[154:157], v[138:141], v[96:111]
	v_mfma_f32_32x32x16_bf16 v[80:95], v[154:157], v[132:135], v[80:95]
	v_mfma_f32_32x32x16_bf16 v[112:127], v[154:157], v[128:131], v[112:127]
	s_setprio 0
	v_lshlrev_b32_e32 v128, 6, v142
	v_lshl_or_b32 v139, v143, 2, v128
	v_lshlrev_b32_e32 v138, 2, v144
	v_cmp_ne_u32_e64 s[4:5], 0, v136
	v_cmp_eq_u32_e32 vcc, 0, v136
	s_barrier
; DI int crow(int reg, int h) { return (reg & 3) + 8 * (reg >> 2) + 4 * h; }
; template <int K, typename Epi>
; DI void gemm_tile_wide(const u16* __restrict__ A, int lda, const u16* __restrict__ Bt, int ldb, int m0, int n0, char* smem, Epi epi) {
;     ...
;   float* Cs = (float*)smem;
; #pragma unroll
;   for (int half = 0; half < 2; ++half) {
;     __syncthreads();
;     if (wn == half) {
; #pragma unroll
;       for (int i = 0; i < 2; ++i)
; #pragma unroll
;         for (int j = 0; j < 4; ++j)
; #pragma unroll
;           for (int e = 0; e < 16; ++e) Cs[(wm * 64 + i * 32 + crow(e, h)) * CS_LD + j * 32 + r] = acc[i][j][e];
;     }
	s_and_saveexec_b64 s[0:1], vcc
	s_cbranch_execz .LBB0_145
	v_mad_u64_u32 v[128:129], s[2:3], v139, s17, v[138:139]
	v_add_u32_e32 v129, 0x400, v128
	v_add_u32_e32 v130, 0x1000, v128
	v_add_u32_e32 v131, 0x1400, v128
	v_add_u32_e32 v132, 0x2000, v128
	v_add_u32_e32 v133, 0x2400, v128
	v_add_u32_e32 v135, 0x3200, v128
	ds_write2_b32 v128, v0, v48 offset1:32
	ds_write2_b32 v128, v1, v49 offset0:132 offset1:164
	ds_write2_b32 v129, v2, v50 offset0:8 offset1:40
	ds_write2_b32 v129, v3, v51 offset0:140 offset1:172
	ds_write2_b32 v130, v4, v52 offset0:32 offset1:64
	ds_write2_b32 v130, v5, v53 offset0:164 offset1:196
	ds_write2_b32 v131, v6, v54 offset0:40 offset1:72
	ds_write2_b32 v131, v7, v55 offset0:172 offset1:204
	ds_write2_b32 v132, v8, v56 offset0:64 offset1:96
	ds_write2_b32 v132, v9, v57 offset0:196 offset1:228
	ds_write2_b32 v133, v10, v58 offset0:72 offset1:104
	ds_write2_b32 v133, v11, v59 offset0:204 offset1:236
	v_add_u32_e32 v134, 0x3000, v128
	ds_write2_b32 v135, v13, v61 offset0:100 offset1:132
	v_add_u32_e32 v135, 0x3400, v128
	v_add_u32_e32 v136, 0x3600, v128
	ds_write2_b32 v134, v12, v60 offset0:96 offset1:128
	ds_write2_b32 v135, v14, v62 offset0:104 offset1:136
	ds_write2_b32 v136, v15, v63 offset0:108 offset1:140
	ds_write2_b32 v128, v16, v64 offset0:64 offset1:96
	ds_write2_b32 v128, v17, v65 offset0:196 offset1:228
	ds_write2_b32 v129, v18, v66 offset0:72 offset1:104
	ds_write2_b32 v129, v19, v67 offset0:204 offset1:236
	ds_write2_b32 v130, v20, v68 offset0:96 offset1:128
	v_add_u32_e32 v129, 0x1200, v128
	ds_write2_b32 v129, v21, v69 offset0:100 offset1:132
	ds_write2_b32 v131, v22, v70 offset0:104 offset1:136
	v_add_u32_e32 v129, 0x1600, v128
	ds_write2_b32 v129, v23, v71 offset0:108 offset1:140
	ds_write2_b32 v132, v24, v72 offset0:128 offset1:160
	ds_write2_b32 v133, v25, v73 offset0:4 offset1:36
	ds_write2_b32 v133, v26, v74 offset0:136 offset1:168
	v_add_u32_e32 v129, 0x2800, v128
	ds_write2_b32 v129, v27, v75 offset0:12 offset1:44
	ds_write2_b32 v134, v28, v76 offset0:160 offset1:192
	ds_write2_b32 v135, v29, v77 offset0:36 offset1:68
	ds_write2_b32 v135, v30, v78 offset0:168 offset1:200
	v_add_u32_e32 v129, 0x3800, v128
	ds_write2_b32 v129, v31, v79 offset0:44 offset1:76
	v_add_u32_e32 v129, 0x4000, v128
	v_add_u32_e32 v130, 0x4400, v128
	v_add_u32_e32 v132, 0x5000, v128
	ds_write2_b32 v129, v32, v96 offset0:128 offset1:160
	ds_write2_b32 v130, v33, v97 offset0:4 offset1:36
	ds_write2_b32 v130, v34, v98 offset0:136 offset1:168
	v_add_u32_e32 v131, 0x4800, v128
	ds_write2_b32 v132, v36, v100 offset0:160 offset1:192
	v_add_u32_e32 v132, 0x5400, v128
	v_add_u32_e32 v134, 0x6000, v128
	ds_write2_b32 v131, v35, v99 offset0:12 offset1:44
	ds_write2_b32 v132, v37, v101 offset0:36 offset1:68
	ds_write2_b32 v132, v38, v102 offset0:168 offset1:200
	v_add_u32_e32 v133, 0x5800, v128
	ds_write2_b32 v134, v40, v104 offset0:192 offset1:224
	v_add_u32_e32 v134, 0x6400, v128
	v_add_u32_e32 v136, 0x7200, v128
	v_add_u32_e32 v140, 0x7600, v128
	ds_write2_b32 v133, v39, v103 offset0:44 offset1:76
	ds_write2_b32 v134, v41, v105 offset0:68 offset1:100
	ds_write2_b32 v134, v42, v106 offset0:200 offset1:232
	v_add_u32_e32 v135, 0x6800, v128
	ds_write2_b32 v136, v44, v108 offset0:96 offset1:128
	v_add_u32_e32 v136, 0x7400, v128
	ds_write2_b32 v140, v46, v110 offset0:104 offset1:136
	v_add_u32_e32 v140, 0x7800, v128
	ds_write2_b32 v135, v43, v107 offset0:76 offset1:108
	ds_write2_b32 v136, v45, v109 offset0:100 offset1:132
	ds_write2_b32 v140, v47, v111 offset0:108 offset1:140
	ds_write2_b32 v129, v80, v112 offset0:192 offset1:224
	ds_write2_b32 v130, v81, v113 offset0:68 offset1:100
	ds_write2_b32 v130, v82, v114 offset0:200 offset1:232
	ds_write2_b32 v131, v83, v115 offset0:76 offset1:108
	v_add_u32_e32 v129, 0x5200, v128
	v_add_u32_e32 v128, 0x5600, v128
	ds_write2_b32 v129, v84, v116 offset0:96 offset1:128
	ds_write2_b32 v132, v85, v117 offset0:100 offset1:132
	ds_write2_b32 v128, v86, v118 offset0:104 offset1:136
	ds_write2_b32 v133, v87, v119 offset0:108 offset1:140
	ds_write2_b32 v134, v88, v120 offset1:32
	ds_write2_b32 v134, v89, v121 offset0:132 offset1:164
	ds_write2_b32 v135, v90, v122 offset0:8 offset1:40
	ds_write2_b32 v135, v91, v123 offset0:140 offset1:172
	ds_write2_b32 v136, v92, v124 offset0:32 offset1:64
	ds_write2_b32 v136, v93, v125 offset0:164 offset1:196
	ds_write2_b32 v140, v94, v126 offset0:40 offset1:72
	ds_write2_b32 v140, v95, v127 offset0:172 offset1:204

; #define MFMA(a, b, c) __builtin_amdgcn_mfma_f32_32x32x16_bf16((a), (b), (c), 0, 0, 0)
; template <int K, typename Epi>
; DI void gemm_tile_wide(const u16* __restrict__ A, int lda, const u16* __restrict__ Bt, int ldb, int m0, int n0, char* smem, Epi epi) {
;     ...
;   auto issue = [&](int slice, int st) {
; #pragma unroll
;     for (int i = 0; i < 4; ++i) {
;       if (i < 2) __builtin_amdgcn_global_load_lds((const unsigned*)(ap[i] + slice * 32), (unsigned*)(ldst + st + i * 4096), 16, 0, 0);
;       __builtin_amdgcn_global_load_lds((const unsigned*)(bp[i] + slice * 32), (unsigned*)(ldst + st + AB + i * 4096), 16, 0, 0);
;     }
;   };
;   __syncthreads();
;   issue(0, 0);
;   for (int kt = 0; kt < NS; ++kt) {
;     asm volatile("s_waitcnt vmcnt(0)" ::: "memory");
;     __syncthreads();
;     const int cur = (kt & 1) * STB;
;     if (kt + 1 < NS) issue(kt + 1, STB - cur);
;     const char* Sg = smem + cur;
;     bf16x8 a[2][2], b[2][4];
; #pragma unroll
;     for (int kk = 0; kk < 2; ++kk) {
; #pragma unroll
;       for (int i = 0; i < 2; ++i) a[kk][i] = *(const bf16x8*)(Sg + aoff[i][kk]);
; #pragma unroll
;       for (int j = 0; j < 4; ++j) b[kk][j] = *(const bf16x8*)(Sg + boff[j][kk]);
;     }
;     __builtin_amdgcn_sched_barrier(0);
;     __builtin_amdgcn_s_setprio(1);
; #pragma unroll
;     for (int kk = 0; kk < 2; ++kk)
; #pragma unroll
;       for (int i = 0; i < 2; ++i)
; #pragma unroll
;         for (int j = 0; j < 4; ++j) acc[i][j] = MFMA(a[kk][i], b[kk][j], acc[i][j]);
;     __builtin_amdgcn_s_setprio(0);
;   }
;   float* Cs = (float*)smem;
; #pragma unroll
;   for (int half = 0; half < 2; ++half) {
;     __syncthreads();
;     if (wn == half) {
.LBB0_643:
	s_bitcmp1_b32 s2, 0
	s_cselect_b32 s3, 0x6000, 0
	v_subrev_u32_e32 v166, s3, v147
	v_add_u32_e32 v167, 0x6000, v166
	v_add_u32_e32 v168, 0x8000, v166
	v_readfirstlane_b32 s28, v167
	v_lshl_add_u64 v[154:155], v[128:129], 0, s[0:1]
	v_add_u32_e32 v169, 0x7000, v166
	v_readfirstlane_b32 s29, v168
	s_mov_b32 m0, s28
	s_waitcnt vmcnt(0)
	s_waitcnt lgkmcnt(0)
	s_barrier
	v_lshl_add_u64 v[156:157], v[130:131], 0, s[100:101]
	v_add_u32_e32 v170, 0x9000, v166
	v_readfirstlane_b32 s30, v169
	global_load_lds_dwordx4 v[154:155], off
	s_mov_b32 m0, s29
	v_lshl_add_u64 v[158:159], v[132:133], 0, s[0:1]
	v_add_u32_e32 v171, 0xa000, v166
	v_readfirstlane_b32 s31, v170
	global_load_lds_dwordx4 v[156:157], off
	s_mov_b32 m0, s30
	v_lshl_add_u64 v[160:161], v[134:135], 0, s[100:101]
	v_add_u32_e32 v166, 0xb000, v166
	v_readfirstlane_b32 s33, v171
	global_load_lds_dwordx4 v[158:159], off
	s_mov_b32 m0, s31
	v_lshl_add_u64 v[162:163], v[138:139], 0, s[100:101]
	v_readfirstlane_b32 s34, v166
	global_load_lds_dwordx4 v[160:161], off
	s_mov_b32 m0, s33
	v_lshl_add_u64 v[164:165], v[140:141], 0, s[100:101]
	global_load_lds_dwordx4 v[162:163], off
	s_mov_b32 m0, s34
	v_add_u32_e32 v158, s3, v145
	global_load_lds_dwordx4 v[164:165], off
	v_add_u32_e32 v162, s3, v148
	v_add_u32_e32 v174, s3, v149
	v_add_u32_e32 v182, s3, v146
	v_add_u32_e32 v188, s3, v150
	v_add_u32_e32 v192, s3, v151
	v_add_u32_e32 v196, s3, v152
	v_add_u32_e32 v200, s3, v153
	ds_read_b128 v[154:157], v158
	ds_read_b128 v[158:161], v158 offset:2048
	ds_read_b128 v[162:165], v162 offset:8192
	ds_read_b128 v[166:169], v174 offset:2048
	ds_read_b128 v[170:173], v174 offset:4096
	ds_read_b128 v[174:177], v174 offset:6144
	ds_read_b128 v[178:181], v182
	ds_read_b128 v[182:185], v182 offset:2048
	ds_read_b128 v[188:191], v188 offset:8192
	ds_read_b128 v[192:195], v192 offset:8192
	ds_read_b128 v[196:199], v196 offset:8192
	ds_read_b128 v[200:203], v200 offset:8192
	s_add_i32 s2, s2, 1
	s_setprio 1
	s_waitcnt lgkmcnt(9)
	v_mfma_f32_32x32x16_bf16 v[0:15], v[154:157], v[162:165], v[0:15]
	s_waitcnt lgkmcnt(8)
	v_mfma_f32_32x32x16_bf16 v[48:63], v[154:157], v[166:169], v[48:63]
	s_waitcnt lgkmcnt(7)
	v_mfma_f32_32x32x16_bf16 v[16:31], v[154:157], v[170:173], v[16:31]
	s_waitcnt lgkmcnt(6)
	v_mfma_f32_32x32x16_bf16 v[64:79], v[154:157], v[174:177], v[64:79]
	v_mfma_f32_32x32x16_bf16 v[32:47], v[158:161], v[162:165], v[32:47]
	v_mfma_f32_32x32x16_bf16 v[96:111], v[158:161], v[166:169], v[96:111]
	v_mfma_f32_32x32x16_bf16 v[80:95], v[158:161], v[170:173], v[80:95]
	v_mfma_f32_32x32x16_bf16 v[112:127], v[158:161], v[174:177], v[112:127]
	s_waitcnt lgkmcnt(3)
	v_mfma_f32_32x32x16_bf16 v[0:15], v[178:181], v[188:191], v[0:15]
	s_waitcnt lgkmcnt(2)
	v_mfma_f32_32x32x16_bf16 v[48:63], v[178:181], v[192:195], v[48:63]
	s_waitcnt lgkmcnt(1)
	v_mfma_f32_32x32x16_bf16 v[16:31], v[178:181], v[196:199], v[16:31]
	s_waitcnt lgkmcnt(0)
	v_mfma_f32_32x32x16_bf16 v[64:79], v[178:181], v[200:203], v[64:79]
	v_mfma_f32_32x32x16_bf16 v[32:47], v[182:185], v[188:191], v[32:47]
	v_mfma_f32_32x32x16_bf16 v[96:111], v[182:185], v[192:195], v[96:111]
	v_mfma_f32_32x32x16_bf16 v[80:95], v[182:185], v[196:199], v[80:95]
	v_mfma_f32_32x32x16_bf16 v[112:127], v[182:185], v[200:203], v[112:127]
	s_setprio 0
	s_add_u32 s0, s0, 64
	s_addc_u32 s1, s1, 0
	s_add_u32 s100, s100, 0x10000
	s_addc_u32 s101, s101, 0
	s_cmpk_eq_i32 s0, 0x7c0
	s_cbranch_scc0 .LBB0_643
	s_waitcnt vmcnt(0)
	s_waitcnt vmcnt(0)
	s_barrier
	ds_read_b128 v[128:131], v153 offset:32768
	ds_read_b128 v[132:135], v152 offset:32768
	ds_read_b128 v[138:141], v151 offset:32768
	ds_read_b128 v[150:153], v150 offset:32768
	ds_read_b128 v[154:157], v146 offset:26624
	ds_read_b128 v[158:161], v146 offset:24576
	ds_read_b128 v[162:165], v149 offset:30720
	ds_read_b128 v[166:169], v149 offset:28672
	ds_read_b128 v[170:173], v149 offset:26624
	ds_read_b128 v[146:149], v148 offset:32768
	ds_read_b128 v[174:177], v145 offset:26624
	ds_read_b128 v[178:181], v145 offset:24576
	s_setprio 1
	s_waitcnt lgkmcnt(0)
	v_mfma_f32_32x32x16_bf16 v[0:15], v[178:181], v[146:149], v[0:15]
	v_mfma_f32_32x32x16_bf16 v[48:63], v[178:181], v[170:173], v[48:63]
	v_mfma_f32_32x32x16_bf16 v[16:31], v[178:181], v[166:169], v[16:31]
	v_mfma_f32_32x32x16_bf16 v[64:79], v[178:181], v[162:165], v[64:79]
	v_mfma_f32_32x32x16_bf16 v[32:47], v[174:177], v[146:149], v[32:47]
	v_mfma_f32_32x32x16_bf16 v[96:111], v[174:177], v[170:173], v[96:111]
	v_mfma_f32_32x32x16_bf16 v[80:95], v[174:177], v[166:169], v[80:95]
	v_mfma_f32_32x32x16_bf16 v[112:127], v[174:177], v[162:165], v[112:127]
	v_mfma_f32_32x32x16_bf16 v[0:15], v[158:161], v[150:153], v[0:15]
	v_mfma_f32_32x32x16_bf16 v[48:63], v[158:161], v[138:141], v[48:63]
	v_mfma_f32_32x32x16_bf16 v[16:31], v[158:161], v[132:135], v[16:31]
	v_mfma_f32_32x32x16_bf16 v[64:79], v[158:161], v[128:131], v[64:79]
	v_mfma_f32_32x32x16_bf16 v[32:47], v[154:157], v[150:153], v[32:47]
	v_mfma_f32_32x32x16_bf16 v[96:111], v[154:157], v[138:141], v[96:111]
	v_mfma_f32_32x32x16_bf16 v[80:95], v[154:157], v[132:135], v[80:95]
	v_mfma_f32_32x32x16_bf16 v[112:127], v[154:157], v[128:131], v[112:127]
	s_setprio 0
	v_lshlrev_b32_e32 v128, 6, v142
	v_lshl_or_b32 v139, v143, 2, v128
	v_lshlrev_b32_e32 v138, 2, v144
	v_cmp_ne_u32_e32 vcc, 0, v136
	v_cmp_eq_u32_e64 s[0:1], 0, v136
	s_barrier
; DI int crow(int reg, int h) { return (reg & 3) + 8 * (reg >> 2) + 4 * h; }
; template <int K, typename Epi>
; DI void gemm_tile_wide(const u16* __restrict__ A, int lda, const u16* __restrict__ Bt, int ldb, int m0, int n0, char* smem, Epi epi) {
;     ...
;   float* Cs = (float*)smem;
; #pragma unroll
;   for (int half = 0; half < 2; ++half) {
;     __syncthreads();
;     if (wn == half) {
; #pragma unroll
;       for (int i = 0; i < 2; ++i)
; #pragma unroll
;         for (int j = 0; j < 4; ++j)
; #pragma unroll
;           for (int e = 0; e < 16; ++e) Cs[(wm * 64 + i * 32 + crow(e, h)) * CS_LD + j * 32 + r] = acc[i][j][e];
;     }
	s_and_saveexec_b64 s[2:3], s[0:1]
	s_cbranch_execz .LBB0_646
	v_mad_u64_u32 v[128:129], s[0:1], v139, s24, v[138:139]
	v_add_u32_e32 v129, 0x400, v128
	v_add_u32_e32 v130, 0x1000, v128
	v_add_u32_e32 v131, 0x1400, v128
	v_add_u32_e32 v132, 0x2000, v128
	v_add_u32_e32 v133, 0x2400, v128
	v_add_u32_e32 v135, 0x3200, v128
	ds_write2_b32 v128, v0, v48 offset1:32
	ds_write2_b32 v128, v1, v49 offset0:132 offset1:164
	ds_write2_b32 v129, v2, v50 offset0:8 offset1:40
	ds_write2_b32 v129, v3, v51 offset0:140 offset1:172
	ds_write2_b32 v130, v4, v52 offset0:32 offset1:64
	ds_write2_b32 v130, v5, v53 offset0:164 offset1:196
	ds_write2_b32 v131, v6, v54 offset0:40 offset1:72
	ds_write2_b32 v131, v7, v55 offset0:172 offset1:204
	ds_write2_b32 v132, v8, v56 offset0:64 offset1:96
	ds_write2_b32 v132, v9, v57 offset0:196 offset1:228
	ds_write2_b32 v133, v10, v58 offset0:72 offset1:104
	ds_write2_b32 v133, v11, v59 offset0:204 offset1:236
	v_add_u32_e32 v134, 0x3000, v128
	ds_write2_b32 v135, v13, v61 offset0:100 offset1:132
	v_add_u32_e32 v135, 0x3400, v128
	v_add_u32_e32 v136, 0x3600, v128
	ds_write2_b32 v134, v12, v60 offset0:96 offset1:128
	ds_write2_b32 v135, v14, v62 offset0:104 offset1:136
	ds_write2_b32 v136, v15, v63 offset0:108 offset1:140
	ds_write2_b32 v128, v16, v64 offset0:64 offset1:96
	ds_write2_b32 v128, v17, v65 offset0:196 offset1:228
	ds_write2_b32 v129, v18, v66 offset0:72 offset1:104
	ds_write2_b32 v129, v19, v67 offset0:204 offset1:236
	ds_write2_b32 v130, v20, v68 offset0:96 offset1:128
	v_add_u32_e32 v129, 0x1200, v128
	ds_write2_b32 v129, v21, v69 offset0:100 offset1:132
	ds_write2_b32 v131, v22, v70 offset0:104 offset1:136
	v_add_u32_e32 v129, 0x1600, v128
	ds_write2_b32 v129, v23, v71 offset0:108 offset1:140
	ds_write2_b32 v132, v24, v72 offset0:128 offset1:160
	ds_write2_b32 v133, v25, v73 offset0:4 offset1:36
	ds_write2_b32 v133, v26, v74 offset0:136 offset1:168
	v_add_u32_e32 v129, 0x2800, v128
	ds_write2_b32 v129, v27, v75 offset0:12 offset1:44
	ds_write2_b32 v134, v28, v76 offset0:160 offset1:192
	ds_write2_b32 v135, v29, v77 offset0:36 offset1:68
	ds_write2_b32 v135, v30, v78 offset0:168 offset1:200
	v_add_u32_e32 v129, 0x3800, v128
	ds_write2_b32 v129, v31, v79 offset0:44 offset1:76
	v_add_u32_e32 v129, 0x4000, v128
	v_add_u32_e32 v130, 0x4400, v128
	v_add_u32_e32 v132, 0x5000, v128
	ds_write2_b32 v129, v32, v96 offset0:128 offset1:160
	ds_write2_b32 v130, v33, v97 offset0:4 offset1:36
	ds_write2_b32 v130, v34, v98 offset0:136 offset1:168
	v_add_u32_e32 v131, 0x4800, v128
	ds_write2_b32 v132, v36, v100 offset0:160 offset1:192
	v_add_u32_e32 v132, 0x5400, v128
	v_add_u32_e32 v134, 0x6000, v128
	ds_write2_b32 v131, v35, v99 offset0:12 offset1:44
	ds_write2_b32 v132, v37, v101 offset0:36 offset1:68
	ds_write2_b32 v132, v38, v102 offset0:168 offset1:200
	v_add_u32_e32 v133, 0x5800, v128
	ds_write2_b32 v134, v40, v104 offset0:192 offset1:224
	v_add_u32_e32 v134, 0x6400, v128
	v_add_u32_e32 v136, 0x7200, v128
	v_add_u32_e32 v140, 0x7600, v128
	ds_write2_b32 v133, v39, v103 offset0:44 offset1:76
	ds_write2_b32 v134, v41, v105 offset0:68 offset1:100
	ds_write2_b32 v134, v42, v106 offset0:200 offset1:232
	v_add_u32_e32 v135, 0x6800, v128
	ds_write2_b32 v136, v44, v108 offset0:96 offset1:128
	v_add_u32_e32 v136, 0x7400, v128
	ds_write2_b32 v140, v46, v110 offset0:104 offset1:136
	v_add_u32_e32 v140, 0x7800, v128
	ds_write2_b32 v135, v43, v107 offset0:76 offset1:108
	ds_write2_b32 v136, v45, v109 offset0:100 offset1:132
	ds_write2_b32 v140, v47, v111 offset0:108 offset1:140
	ds_write2_b32 v129, v80, v112 offset0:192 offset1:224
	ds_write2_b32 v130, v81, v113 offset0:68 offset1:100
	ds_write2_b32 v130, v82, v114 offset0:200 offset1:232
	ds_write2_b32 v131, v83, v115 offset0:76 offset1:108
	v_add_u32_e32 v129, 0x5200, v128
	v_add_u32_e32 v128, 0x5600, v128
	ds_write2_b32 v129, v84, v116 offset0:96 offset1:128
	ds_write2_b32 v132, v85, v117 offset0:100 offset1:132
	ds_write2_b32 v128, v86, v118 offset0:104 offset1:136
	ds_write2_b32 v133, v87, v119 offset0:108 offset1:140
	ds_write2_b32 v134, v88, v120 offset1:32
	ds_write2_b32 v134, v89, v121 offset0:132 offset1:164
	ds_write2_b32 v135, v90, v122 offset0:8 offset1:40
	ds_write2_b32 v135, v91, v123 offset0:140 offset1:172
	ds_write2_b32 v136, v92, v124 offset0:32 offset1:64
	ds_write2_b32 v136, v93, v125 offset0:164 offset1:196
	ds_write2_b32 v140, v94, v126 offset0:40 offset1:72
	ds_write2_b32 v140, v95, v127 offset0:172 offset1:204

; #define MFMA(a, b, c) __builtin_amdgcn_mfma_f32_32x32x16_bf16((a), (b), (c), 0, 0, 0)
; template <int K, typename Epi>
; DI void gemm_tile_wide(const u16* __restrict__ A, int lda, const u16* __restrict__ Bt, int ldb, int m0, int n0, char* smem, Epi epi) {
;     ...
;   auto issue = [&](int slice, int st) {
; #pragma unroll
;     for (int i = 0; i < 4; ++i) {
;       if (i < 2) __builtin_amdgcn_global_load_lds((const unsigned*)(ap[i] + slice * 32), (unsigned*)(ldst + st + i * 4096), 16, 0, 0);
;       __builtin_amdgcn_global_load_lds((const unsigned*)(bp[i] + slice * 32), (unsigned*)(ldst + st + AB + i * 4096), 16, 0, 0);
;     }
;   };
;   __syncthreads();
;   issue(0, 0);
;   for (int kt = 0; kt < NS; ++kt) {
;     asm volatile("s_waitcnt vmcnt(0)" ::: "memory");
;     __syncthreads();
;     const int cur = (kt & 1) * STB;
;     if (kt + 1 < NS) issue(kt + 1, STB - cur);
;     const char* Sg = smem + cur;
;     bf16x8 a[2][2], b[2][4];
; #pragma unroll
;     for (int kk = 0; kk < 2; ++kk) {
; #pragma unroll
;       for (int i = 0; i < 2; ++i) a[kk][i] = *(const bf16x8*)(Sg + aoff[i][kk]);
; #pragma unroll
;       for (int j = 0; j < 4; ++j) b[kk][j] = *(const bf16x8*)(Sg + boff[j][kk]);
;     }
;     __builtin_amdgcn_sched_barrier(0);
;     __builtin_amdgcn_s_setprio(1);
; #pragma unroll
;     for (int kk = 0; kk < 2; ++kk)
; #pragma unroll
;       for (int i = 0; i < 2; ++i)
; #pragma unroll
;         for (int j = 0; j < 4; ++j) acc[i][j] = MFMA(a[kk][i], b[kk][j], acc[i][j]);
;     __builtin_amdgcn_s_setprio(0);
;   }
;   float* Cs = (float*)smem;
; #pragma unroll
;   for (int half = 0; half < 2; ++half) {
;     __syncthreads();
;     if (wn == half) {
.LBB0_927:
	s_bitcmp1_b32 s3, 0
	s_cselect_b32 s5, 0x6000, 0
	v_subrev_u32_e32 v166, s5, v147
	v_add_u32_e32 v167, 0x6000, v166
	v_add_u32_e32 v168, 0x8000, v166
	v_readfirstlane_b32 s6, v167
	v_lshl_add_u64 v[154:155], v[128:129], 0, s[0:1]
	v_add_u32_e32 v169, 0x7000, v166
	v_readfirstlane_b32 s7, v168
	s_mov_b32 m0, s6
	s_waitcnt vmcnt(0)
	s_waitcnt vmcnt(0) lgkmcnt(0)
	s_barrier
	v_lshl_add_u64 v[156:157], v[130:131], 0, s[100:101]
	v_add_u32_e32 v170, 0x9000, v166
	v_readfirstlane_b32 s8, v169
	global_load_lds_dwordx4 v[154:155], off
	s_mov_b32 m0, s7
	v_lshl_add_u64 v[158:159], v[134:135], 0, s[0:1]
	v_add_u32_e32 v171, 0xa000, v166
	v_readfirstlane_b32 s9, v170
	global_load_lds_dwordx4 v[156:157], off
	s_mov_b32 m0, s8
	v_lshl_add_u64 v[160:161], v[136:137], 0, s[100:101]
	v_add_u32_e32 v166, 0xb000, v166
	v_readfirstlane_b32 s18, v171
	global_load_lds_dwordx4 v[158:159], off
	s_mov_b32 m0, s9
	v_lshl_add_u64 v[162:163], v[138:139], 0, s[100:101]
	v_readfirstlane_b32 s19, v166
	global_load_lds_dwordx4 v[160:161], off
	s_mov_b32 m0, s18
	v_lshl_add_u64 v[164:165], v[140:141], 0, s[100:101]
	global_load_lds_dwordx4 v[162:163], off
	s_mov_b32 m0, s19
	v_add_u32_e32 v158, s5, v145
	global_load_lds_dwordx4 v[164:165], off
	v_add_u32_e32 v162, s5, v148
	v_add_u32_e32 v174, s5, v149
	v_add_u32_e32 v182, s5, v146
	v_add_u32_e32 v188, s5, v150
	v_add_u32_e32 v192, s5, v151
	v_add_u32_e32 v196, s5, v152
	v_add_u32_e32 v200, s5, v153
	ds_read_b128 v[154:157], v158
	ds_read_b128 v[158:161], v158 offset:2048
	ds_read_b128 v[162:165], v162 offset:8192
	ds_read_b128 v[166:169], v174 offset:2048
	ds_read_b128 v[170:173], v174 offset:4096
	ds_read_b128 v[174:177], v174 offset:6144
	ds_read_b128 v[178:181], v182
	ds_read_b128 v[182:185], v182 offset:2048
	ds_read_b128 v[188:191], v188 offset:8192
	ds_read_b128 v[192:195], v192 offset:8192
	ds_read_b128 v[196:199], v196 offset:8192
	ds_read_b128 v[200:203], v200 offset:8192
	s_add_i32 s3, s3, 1
	s_setprio 1
	s_waitcnt lgkmcnt(9)
	v_mfma_f32_32x32x16_bf16 v[0:15], v[154:157], v[162:165], v[0:15]
	s_waitcnt lgkmcnt(8)
	v_mfma_f32_32x32x16_bf16 v[48:63], v[154:157], v[166:169], v[48:63]
	s_waitcnt lgkmcnt(7)
	v_mfma_f32_32x32x16_bf16 v[16:31], v[154:157], v[170:173], v[16:31]
	s_waitcnt lgkmcnt(6)
	v_mfma_f32_32x32x16_bf16 v[64:79], v[154:157], v[174:177], v[64:79]
	v_mfma_f32_32x32x16_bf16 v[32:47], v[158:161], v[162:165], v[32:47]
	v_mfma_f32_32x32x16_bf16 v[96:111], v[158:161], v[166:169], v[96:111]
	v_mfma_f32_32x32x16_bf16 v[80:95], v[158:161], v[170:173], v[80:95]
	v_mfma_f32_32x32x16_bf16 v[112:127], v[158:161], v[174:177], v[112:127]
	s_waitcnt lgkmcnt(3)
	v_mfma_f32_32x32x16_bf16 v[0:15], v[178:181], v[188:191], v[0:15]
	s_waitcnt lgkmcnt(2)
	v_mfma_f32_32x32x16_bf16 v[48:63], v[178:181], v[192:195], v[48:63]
	s_waitcnt lgkmcnt(1)
	v_mfma_f32_32x32x16_bf16 v[16:31], v[178:181], v[196:199], v[16:31]
	s_waitcnt lgkmcnt(0)
	v_mfma_f32_32x32x16_bf16 v[64:79], v[178:181], v[200:203], v[64:79]
	v_mfma_f32_32x32x16_bf16 v[32:47], v[182:185], v[188:191], v[32:47]
	v_mfma_f32_32x32x16_bf16 v[96:111], v[182:185], v[192:195], v[96:111]
	v_mfma_f32_32x32x16_bf16 v[80:95], v[182:185], v[196:199], v[80:95]
	v_mfma_f32_32x32x16_bf16 v[112:127], v[182:185], v[200:203], v[112:127]
	s_setprio 0
	s_add_u32 s0, s0, 64
	s_addc_u32 s1, s1, 0
	s_add_u32 s100, s100, 0x40000
	s_addc_u32 s101, s101, 0
	s_cmpk_eq_i32 s0, 0x7c0
	s_cbranch_scc0 .LBB0_927
	s_waitcnt vmcnt(0)
	s_waitcnt vmcnt(0)
	s_barrier
	ds_read_b128 v[128:131], v153 offset:32768
	ds_read_b128 v[134:137], v152 offset:32768
	ds_read_b128 v[138:141], v151 offset:32768
	ds_read_b128 v[150:153], v150 offset:32768
	ds_read_b128 v[154:157], v146 offset:26624
	ds_read_b128 v[158:161], v146 offset:24576
	ds_read_b128 v[162:165], v149 offset:30720
	ds_read_b128 v[166:169], v149 offset:28672
	ds_read_b128 v[170:173], v149 offset:26624
	ds_read_b128 v[146:149], v148 offset:32768
	ds_read_b128 v[174:177], v145 offset:26624
	ds_read_b128 v[178:181], v145 offset:24576
	s_setprio 1
	s_waitcnt lgkmcnt(0)
	v_mfma_f32_32x32x16_bf16 v[0:15], v[178:181], v[146:149], v[0:15]
	v_mfma_f32_32x32x16_bf16 v[48:63], v[178:181], v[170:173], v[48:63]
	v_mfma_f32_32x32x16_bf16 v[16:31], v[178:181], v[166:169], v[16:31]
	v_mfma_f32_32x32x16_bf16 v[64:79], v[178:181], v[162:165], v[64:79]
	v_mfma_f32_32x32x16_bf16 v[32:47], v[174:177], v[146:149], v[32:47]
	v_mfma_f32_32x32x16_bf16 v[96:111], v[174:177], v[170:173], v[96:111]
	v_mfma_f32_32x32x16_bf16 v[80:95], v[174:177], v[166:169], v[80:95]
	v_mfma_f32_32x32x16_bf16 v[112:127], v[174:177], v[162:165], v[112:127]
	v_mfma_f32_32x32x16_bf16 v[0:15], v[158:161], v[150:153], v[0:15]
	v_mfma_f32_32x32x16_bf16 v[48:63], v[158:161], v[138:141], v[48:63]
	v_mfma_f32_32x32x16_bf16 v[16:31], v[158:161], v[134:137], v[16:31]
	v_mfma_f32_32x32x16_bf16 v[64:79], v[158:161], v[128:131], v[64:79]
	v_mfma_f32_32x32x16_bf16 v[32:47], v[154:157], v[150:153], v[32:47]
	v_mfma_f32_32x32x16_bf16 v[96:111], v[154:157], v[138:141], v[96:111]
	v_mfma_f32_32x32x16_bf16 v[80:95], v[154:157], v[134:137], v[80:95]
	v_mfma_f32_32x32x16_bf16 v[112:127], v[154:157], v[128:131], v[112:127]
	s_setprio 0
	v_lshlrev_b32_e32 v128, 6, v142
	v_lshl_or_b32 v135, v143, 2, v128
	v_lshlrev_b32_e32 v134, 2, v144
	v_cmp_ne_u32_e64 s[8:9], 0, v132
	v_cmp_eq_u32_e32 vcc, 0, v132
	s_barrier
; DI int crow(int reg, int h) { return (reg & 3) + 8 * (reg >> 2) + 4 * h; }
; template <int K, typename Epi>
; DI void gemm_tile_wide(const u16* __restrict__ A, int lda, const u16* __restrict__ Bt, int ldb, int m0, int n0, char* smem, Epi epi) {
;     ...
;   float* Cs = (float*)smem;
; #pragma unroll
;   for (int half = 0; half < 2; ++half) {
;     __syncthreads();
;     if (wn == half) {
; #pragma unroll
;       for (int i = 0; i < 2; ++i)
; #pragma unroll
;         for (int j = 0; j < 4; ++j)
; #pragma unroll
;           for (int e = 0; e < 16; ++e) Cs[(wm * 64 + i * 32 + crow(e, h)) * CS_LD + j * 32 + r] = acc[i][j][e];
;     }
	s_and_saveexec_b64 s[0:1], vcc
	s_cbranch_execz .LBB0_930
	v_mad_u64_u32 v[128:129], s[6:7], v135, s52, v[134:135]
	v_add_u32_e32 v129, 0x400, v128
	v_add_u32_e32 v130, 0x1000, v128
	v_add_u32_e32 v131, 0x1400, v128
	v_add_u32_e32 v132, 0x2000, v128
	v_add_u32_e32 v136, 0x2400, v128
	v_add_u32_e32 v138, 0x3200, v128
	ds_write2_b32 v128, v0, v48 offset1:32
	ds_write2_b32 v128, v1, v49 offset0:132 offset1:164
	ds_write2_b32 v129, v2, v50 offset0:8 offset1:40
	ds_write2_b32 v129, v3, v51 offset0:140 offset1:172
	ds_write2_b32 v130, v4, v52 offset0:32 offset1:64
	ds_write2_b32 v130, v5, v53 offset0:164 offset1:196
	ds_write2_b32 v131, v6, v54 offset0:40 offset1:72
	ds_write2_b32 v131, v7, v55 offset0:172 offset1:204
	ds_write2_b32 v132, v8, v56 offset0:64 offset1:96
	ds_write2_b32 v132, v9, v57 offset0:196 offset1:228
	ds_write2_b32 v136, v10, v58 offset0:72 offset1:104
	ds_write2_b32 v136, v11, v59 offset0:204 offset1:236
	v_add_u32_e32 v137, 0x3000, v128
	ds_write2_b32 v138, v13, v61 offset0:100 offset1:132
	v_add_u32_e32 v138, 0x3400, v128
	v_add_u32_e32 v139, 0x3600, v128
	ds_write2_b32 v137, v12, v60 offset0:96 offset1:128
	ds_write2_b32 v138, v14, v62 offset0:104 offset1:136
	ds_write2_b32 v139, v15, v63 offset0:108 offset1:140
	ds_write2_b32 v128, v16, v64 offset0:64 offset1:96
	ds_write2_b32 v128, v17, v65 offset0:196 offset1:228
	ds_write2_b32 v129, v18, v66 offset0:72 offset1:104
	ds_write2_b32 v129, v19, v67 offset0:204 offset1:236
	ds_write2_b32 v130, v20, v68 offset0:96 offset1:128
	v_add_u32_e32 v129, 0x1200, v128
	ds_write2_b32 v129, v21, v69 offset0:100 offset1:132
	ds_write2_b32 v131, v22, v70 offset0:104 offset1:136
	v_add_u32_e32 v129, 0x1600, v128
	ds_write2_b32 v129, v23, v71 offset0:108 offset1:140
	ds_write2_b32 v132, v24, v72 offset0:128 offset1:160
	ds_write2_b32 v136, v25, v73 offset0:4 offset1:36
	ds_write2_b32 v136, v26, v74 offset0:136 offset1:168
	v_add_u32_e32 v129, 0x2800, v128
	ds_write2_b32 v129, v27, v75 offset0:12 offset1:44
	ds_write2_b32 v137, v28, v76 offset0:160 offset1:192
	ds_write2_b32 v138, v29, v77 offset0:36 offset1:68
	ds_write2_b32 v138, v30, v78 offset0:168 offset1:200
	v_add_u32_e32 v129, 0x3800, v128
	ds_write2_b32 v129, v31, v79 offset0:44 offset1:76
	v_add_u32_e32 v129, 0x4000, v128
	v_add_u32_e32 v130, 0x4400, v128
	v_add_u32_e32 v132, 0x5000, v128
	ds_write2_b32 v129, v32, v96 offset0:128 offset1:160
	ds_write2_b32 v130, v33, v97 offset0:4 offset1:36
	ds_write2_b32 v130, v34, v98 offset0:136 offset1:168
	v_add_u32_e32 v131, 0x4800, v128
	ds_write2_b32 v132, v36, v100 offset0:160 offset1:192
	v_add_u32_e32 v132, 0x5400, v128
	v_add_u32_e32 v137, 0x6000, v128
	ds_write2_b32 v131, v35, v99 offset0:12 offset1:44
	ds_write2_b32 v132, v37, v101 offset0:36 offset1:68
	ds_write2_b32 v132, v38, v102 offset0:168 offset1:200
	v_add_u32_e32 v136, 0x5800, v128
	ds_write2_b32 v137, v40, v104 offset0:192 offset1:224
	v_add_u32_e32 v137, 0x6400, v128
	v_add_u32_e32 v139, 0x7200, v128
	v_add_u32_e32 v140, 0x7600, v128
	ds_write2_b32 v136, v39, v103 offset0:44 offset1:76
	ds_write2_b32 v137, v41, v105 offset0:68 offset1:100
	ds_write2_b32 v137, v42, v106 offset0:200 offset1:232
	v_add_u32_e32 v138, 0x6800, v128
	ds_write2_b32 v139, v44, v108 offset0:96 offset1:128
	v_add_u32_e32 v139, 0x7400, v128
	ds_write2_b32 v140, v46, v110 offset0:104 offset1:136
	v_add_u32_e32 v140, 0x7800, v128
	ds_write2_b32 v138, v43, v107 offset0:76 offset1:108
	ds_write2_b32 v139, v45, v109 offset0:100 offset1:132
	ds_write2_b32 v140, v47, v111 offset0:108 offset1:140
	ds_write2_b32 v129, v80, v112 offset0:192 offset1:224
	ds_write2_b32 v130, v81, v113 offset0:68 offset1:100
	ds_write2_b32 v130, v82, v114 offset0:200 offset1:232
	ds_write2_b32 v131, v83, v115 offset0:76 offset1:108
	v_add_u32_e32 v129, 0x5200, v128
	v_add_u32_e32 v128, 0x5600, v128
	ds_write2_b32 v129, v84, v116 offset0:96 offset1:128
	ds_write2_b32 v132, v85, v117 offset0:100 offset1:132
	ds_write2_b32 v128, v86, v118 offset0:104 offset1:136
	ds_write2_b32 v136, v87, v119 offset0:108 offset1:140
	ds_write2_b32 v137, v88, v120 offset1:32
	ds_write2_b32 v137, v89, v121 offset0:132 offset1:164
	ds_write2_b32 v138, v90, v122 offset0:8 offset1:40
	ds_write2_b32 v138, v91, v123 offset0:140 offset1:172
	ds_write2_b32 v139, v92, v124 offset0:32 offset1:64
	ds_write2_b32 v139, v93, v125 offset0:164 offset1:196
	ds_write2_b32 v140, v94, v126 offset0:40 offset1:72
	ds_write2_b32 v140, v95, v127 offset0:172 offset1:204

; #define MFMA(a, b, c) __builtin_amdgcn_mfma_f32_32x32x16_bf16((a), (b), (c), 0, 0, 0)
; template <int K, typename Epi>
; DI void gemm_tile_wide(const u16* __restrict__ A, int lda, const u16* __restrict__ Bt, int ldb, int m0, int n0, char* smem, Epi epi) {
;     ...
;   auto issue = [&](int slice, int st) {
; #pragma unroll
;     for (int i = 0; i < 4; ++i) {
;       if (i < 2) __builtin_amdgcn_global_load_lds((const unsigned*)(ap[i] + slice * 32), (unsigned*)(ldst + st + i * 4096), 16, 0, 0);
;       __builtin_amdgcn_global_load_lds((const unsigned*)(bp[i] + slice * 32), (unsigned*)(ldst + st + AB + i * 4096), 16, 0, 0);
;     }
;   };
;   __syncthreads();
;   issue(0, 0);
;   for (int kt = 0; kt < NS; ++kt) {
;     asm volatile("s_waitcnt vmcnt(0)" ::: "memory");
;     __syncthreads();
;     const int cur = (kt & 1) * STB;
;     if (kt + 1 < NS) issue(kt + 1, STB - cur);
;     const char* Sg = smem + cur;
;     bf16x8 a[2][2], b[2][4];
; #pragma unroll
;     for (int kk = 0; kk < 2; ++kk) {
; #pragma unroll
;       for (int i = 0; i < 2; ++i) a[kk][i] = *(const bf16x8*)(Sg + aoff[i][kk]);
; #pragma unroll
;       for (int j = 0; j < 4; ++j) b[kk][j] = *(const bf16x8*)(Sg + boff[j][kk]);
;     }
;     __builtin_amdgcn_sched_barrier(0);
;     __builtin_amdgcn_s_setprio(1);
; #pragma unroll
;     for (int kk = 0; kk < 2; ++kk)
; #pragma unroll
;       for (int i = 0; i < 2; ++i)
; #pragma unroll
;         for (int j = 0; j < 4; ++j) acc[i][j] = MFMA(a[kk][i], b[kk][j], acc[i][j]);
;     __builtin_amdgcn_s_setprio(0);
;   }
;   float* Cs = (float*)smem;
; #pragma unroll
;   for (int half = 0; half < 2; ++half) {
;     __syncthreads();
;     if (wn == half) {
.LBB0_2051:
	s_bitcmp1_b32 s2, 0
	s_cselect_b32 s3, 0x6000, 0
	v_subrev_u32_e32 v166, s3, v147
	v_add_u32_e32 v167, 0x6000, v166
	v_add_u32_e32 v168, 0x8000, v166
	v_readfirstlane_b32 s29, v167
	v_lshl_add_u64 v[154:155], v[130:131], 0, s[0:1]
	v_add_u32_e32 v169, 0x7000, v166
	v_readfirstlane_b32 s30, v168
	s_mov_b32 m0, s29
	s_waitcnt vmcnt(0)
	s_waitcnt vmcnt(0) lgkmcnt(0)
	s_barrier
	v_lshl_add_u64 v[156:157], v[132:133], 0, s[100:101]
	v_add_u32_e32 v170, 0x9000, v166
	v_readfirstlane_b32 s31, v169
	global_load_lds_dwordx4 v[154:155], off
	s_mov_b32 m0, s30
	v_lshl_add_u64 v[158:159], v[134:135], 0, s[0:1]
	v_add_u32_e32 v171, 0xa000, v166
	v_readfirstlane_b32 s33, v170
	global_load_lds_dwordx4 v[156:157], off
	s_mov_b32 m0, s31
	v_lshl_add_u64 v[160:161], v[136:137], 0, s[100:101]
	v_add_u32_e32 v166, 0xb000, v166
	v_readfirstlane_b32 s34, v171
	global_load_lds_dwordx4 v[158:159], off
	s_mov_b32 m0, s33
	v_lshl_add_u64 v[162:163], v[138:139], 0, s[100:101]
	v_readfirstlane_b32 s35, v166
	global_load_lds_dwordx4 v[160:161], off
	s_mov_b32 m0, s34
	v_lshl_add_u64 v[164:165], v[140:141], 0, s[100:101]
	global_load_lds_dwordx4 v[162:163], off
	s_mov_b32 m0, s35
	v_add_u32_e32 v158, s3, v145
	global_load_lds_dwordx4 v[164:165], off
	v_add_u32_e32 v162, s3, v148
	v_add_u32_e32 v174, s3, v149
	v_add_u32_e32 v182, s3, v146
	v_add_u32_e32 v188, s3, v150
	v_add_u32_e32 v192, s3, v151
	v_add_u32_e32 v196, s3, v152
	v_add_u32_e32 v200, s3, v153
	ds_read_b128 v[154:157], v158
	ds_read_b128 v[158:161], v158 offset:2048
	ds_read_b128 v[162:165], v162 offset:8192
	ds_read_b128 v[166:169], v174 offset:2048
	ds_read_b128 v[170:173], v174 offset:4096
	ds_read_b128 v[174:177], v174 offset:6144
	ds_read_b128 v[178:181], v182
	ds_read_b128 v[182:185], v182 offset:2048
	ds_read_b128 v[188:191], v188 offset:8192
	ds_read_b128 v[192:195], v192 offset:8192
	ds_read_b128 v[196:199], v196 offset:8192
	ds_read_b128 v[200:203], v200 offset:8192
	s_add_i32 s2, s2, 1
	s_setprio 1
	s_waitcnt lgkmcnt(9)
	v_mfma_f32_32x32x16_bf16 v[0:15], v[154:157], v[162:165], v[0:15]
	s_waitcnt lgkmcnt(8)
	v_mfma_f32_32x32x16_bf16 v[48:63], v[154:157], v[166:169], v[48:63]
	s_waitcnt lgkmcnt(7)
	v_mfma_f32_32x32x16_bf16 v[16:31], v[154:157], v[170:173], v[16:31]
	s_waitcnt lgkmcnt(6)
	v_mfma_f32_32x32x16_bf16 v[64:79], v[154:157], v[174:177], v[64:79]
	v_mfma_f32_32x32x16_bf16 v[32:47], v[158:161], v[162:165], v[32:47]
	v_mfma_f32_32x32x16_bf16 v[96:111], v[158:161], v[166:169], v[96:111]
	v_mfma_f32_32x32x16_bf16 v[80:95], v[158:161], v[170:173], v[80:95]
	v_mfma_f32_32x32x16_bf16 v[112:127], v[158:161], v[174:177], v[112:127]
	s_waitcnt lgkmcnt(3)
	v_mfma_f32_32x32x16_bf16 v[0:15], v[178:181], v[188:191], v[0:15]
	s_waitcnt lgkmcnt(2)
	v_mfma_f32_32x32x16_bf16 v[48:63], v[178:181], v[192:195], v[48:63]
	s_waitcnt lgkmcnt(1)
	v_mfma_f32_32x32x16_bf16 v[16:31], v[178:181], v[196:199], v[16:31]
	s_waitcnt lgkmcnt(0)
	v_mfma_f32_32x32x16_bf16 v[64:79], v[178:181], v[200:203], v[64:79]
	v_mfma_f32_32x32x16_bf16 v[32:47], v[182:185], v[188:191], v[32:47]
	v_mfma_f32_32x32x16_bf16 v[96:111], v[182:185], v[192:195], v[96:111]
	v_mfma_f32_32x32x16_bf16 v[80:95], v[182:185], v[196:199], v[80:95]
	v_mfma_f32_32x32x16_bf16 v[112:127], v[182:185], v[200:203], v[112:127]
	s_setprio 0
	s_add_u32 s0, s0, 64
	s_addc_u32 s1, s1, 0
	s_add_u32 s100, s100, 0x10000
	s_addc_u32 s101, s101, 0
	s_cmpk_eq_i32 s0, 0x7c0
	s_cbranch_scc0 .LBB0_2051
	s_waitcnt vmcnt(0)
	s_waitcnt vmcnt(0)
	s_barrier
	ds_read_b128 v[130:133], v153 offset:32768
	ds_read_b128 v[134:137], v152 offset:32768
	ds_read_b128 v[138:141], v151 offset:32768
	ds_read_b128 v[150:153], v150 offset:32768
	ds_read_b128 v[154:157], v146 offset:26624
	ds_read_b128 v[158:161], v146 offset:24576
	ds_read_b128 v[162:165], v149 offset:30720
	ds_read_b128 v[166:169], v149 offset:28672
	ds_read_b128 v[170:173], v149 offset:26624
	ds_read_b128 v[146:149], v148 offset:32768
	ds_read_b128 v[174:177], v145 offset:26624
	ds_read_b128 v[178:181], v145 offset:24576
	s_setprio 1
	s_waitcnt lgkmcnt(0)
	v_mfma_f32_32x32x16_bf16 v[0:15], v[178:181], v[146:149], v[0:15]
	v_mfma_f32_32x32x16_bf16 v[48:63], v[178:181], v[170:173], v[48:63]
	v_mfma_f32_32x32x16_bf16 v[16:31], v[178:181], v[166:169], v[16:31]
	v_mfma_f32_32x32x16_bf16 v[64:79], v[178:181], v[162:165], v[64:79]
	v_mfma_f32_32x32x16_bf16 v[32:47], v[174:177], v[146:149], v[32:47]
	v_mfma_f32_32x32x16_bf16 v[96:111], v[174:177], v[170:173], v[96:111]
	v_mfma_f32_32x32x16_bf16 v[80:95], v[174:177], v[166:169], v[80:95]
	v_mfma_f32_32x32x16_bf16 v[112:127], v[174:177], v[162:165], v[112:127]
	v_mfma_f32_32x32x16_bf16 v[0:15], v[158:161], v[150:153], v[0:15]
	v_mfma_f32_32x32x16_bf16 v[48:63], v[158:161], v[138:141], v[48:63]
	v_mfma_f32_32x32x16_bf16 v[16:31], v[158:161], v[134:137], v[16:31]
	v_mfma_f32_32x32x16_bf16 v[64:79], v[158:161], v[130:133], v[64:79]
	v_mfma_f32_32x32x16_bf16 v[32:47], v[154:157], v[150:153], v[32:47]
	v_mfma_f32_32x32x16_bf16 v[96:111], v[154:157], v[138:141], v[96:111]
	v_mfma_f32_32x32x16_bf16 v[80:95], v[154:157], v[134:137], v[80:95]
	v_mfma_f32_32x32x16_bf16 v[112:127], v[154:157], v[130:133], v[112:127]
	s_setprio 0
	v_lshlrev_b32_e32 v130, 6, v142
	v_lshl_or_b32 v131, v143, 2, v130
	v_lshlrev_b32_e32 v130, 2, v144
	v_cmp_ne_u32_e32 vcc, 0, v128
	v_cmp_eq_u32_e64 s[0:1], 0, v128
	s_barrier
; DI int crow(int reg, int h) { return (reg & 3) + 8 * (reg >> 2) + 4 * h; }
; template <int K, typename Epi>
; DI void gemm_tile_wide(const u16* __restrict__ A, int lda, const u16* __restrict__ Bt, int ldb, int m0, int n0, char* smem, Epi epi) {
;     ...
;   float* Cs = (float*)smem;
; #pragma unroll
;   for (int half = 0; half < 2; ++half) {
;     __syncthreads();
;     if (wn == half) {
; #pragma unroll
;       for (int i = 0; i < 2; ++i)
; #pragma unroll
;         for (int j = 0; j < 4; ++j)
; #pragma unroll
;           for (int e = 0; e < 16; ++e) Cs[(wm * 64 + i * 32 + crow(e, h)) * CS_LD + j * 32 + r] = acc[i][j][e];
;     }
	s_and_saveexec_b64 s[2:3], s[0:1]
	s_cbranch_execz .LBB0_2054
	v_mad_u64_u32 v[132:133], s[0:1], v131, s26, v[130:131]
	v_add_u32_e32 v128, 0x400, v132
	v_add_u32_e32 v133, 0x1000, v132
	v_add_u32_e32 v134, 0x1400, v132
	v_add_u32_e32 v135, 0x2000, v132
	v_add_u32_e32 v136, 0x2400, v132
	v_add_u32_e32 v138, 0x3200, v132
	ds_write2_b32 v132, v0, v48 offset1:32
	ds_write2_b32 v132, v1, v49 offset0:132 offset1:164
	ds_write2_b32 v128, v2, v50 offset0:8 offset1:40
	ds_write2_b32 v128, v3, v51 offset0:140 offset1:172
	ds_write2_b32 v133, v4, v52 offset0:32 offset1:64
	ds_write2_b32 v133, v5, v53 offset0:164 offset1:196
	ds_write2_b32 v134, v6, v54 offset0:40 offset1:72
	ds_write2_b32 v134, v7, v55 offset0:172 offset1:204
	ds_write2_b32 v135, v8, v56 offset0:64 offset1:96
	ds_write2_b32 v135, v9, v57 offset0:196 offset1:228
	ds_write2_b32 v136, v10, v58 offset0:72 offset1:104
	ds_write2_b32 v136, v11, v59 offset0:204 offset1:236
	v_add_u32_e32 v137, 0x3000, v132
	ds_write2_b32 v138, v13, v61 offset0:100 offset1:132
	v_add_u32_e32 v138, 0x3400, v132
	v_add_u32_e32 v139, 0x3600, v132
	ds_write2_b32 v137, v12, v60 offset0:96 offset1:128
	ds_write2_b32 v138, v14, v62 offset0:104 offset1:136
	ds_write2_b32 v139, v15, v63 offset0:108 offset1:140
	ds_write2_b32 v132, v16, v64 offset0:64 offset1:96
	ds_write2_b32 v132, v17, v65 offset0:196 offset1:228
	ds_write2_b32 v128, v18, v66 offset0:72 offset1:104
	ds_write2_b32 v128, v19, v67 offset0:204 offset1:236
	ds_write2_b32 v133, v20, v68 offset0:96 offset1:128
	v_add_u32_e32 v128, 0x1200, v132
	ds_write2_b32 v128, v21, v69 offset0:100 offset1:132
	ds_write2_b32 v134, v22, v70 offset0:104 offset1:136
	v_add_u32_e32 v128, 0x1600, v132
	ds_write2_b32 v128, v23, v71 offset0:108 offset1:140
	ds_write2_b32 v135, v24, v72 offset0:128 offset1:160
	ds_write2_b32 v136, v25, v73 offset0:4 offset1:36
	ds_write2_b32 v136, v26, v74 offset0:136 offset1:168
	v_add_u32_e32 v128, 0x2800, v132
	ds_write2_b32 v128, v27, v75 offset0:12 offset1:44
	ds_write2_b32 v137, v28, v76 offset0:160 offset1:192
	ds_write2_b32 v138, v29, v77 offset0:36 offset1:68
	ds_write2_b32 v138, v30, v78 offset0:168 offset1:200
	v_add_u32_e32 v128, 0x3800, v132
	ds_write2_b32 v128, v31, v79 offset0:44 offset1:76
	v_add_u32_e32 v128, 0x4000, v132
	v_add_u32_e32 v133, 0x4400, v132
	v_add_u32_e32 v135, 0x5000, v132
	ds_write2_b32 v128, v32, v96 offset0:128 offset1:160
	ds_write2_b32 v133, v33, v97 offset0:4 offset1:36
	ds_write2_b32 v133, v34, v98 offset0:136 offset1:168
	v_add_u32_e32 v134, 0x4800, v132
	ds_write2_b32 v135, v36, v100 offset0:160 offset1:192
	v_add_u32_e32 v135, 0x5400, v132
	v_add_u32_e32 v137, 0x6000, v132
	ds_write2_b32 v134, v35, v99 offset0:12 offset1:44
	ds_write2_b32 v135, v37, v101 offset0:36 offset1:68
	ds_write2_b32 v135, v38, v102 offset0:168 offset1:200
	v_add_u32_e32 v136, 0x5800, v132
	ds_write2_b32 v137, v40, v104 offset0:192 offset1:224
	v_add_u32_e32 v137, 0x6400, v132
	v_add_u32_e32 v139, 0x7200, v132
	v_add_u32_e32 v140, 0x7600, v132
	ds_write2_b32 v136, v39, v103 offset0:44 offset1:76
	ds_write2_b32 v137, v41, v105 offset0:68 offset1:100
	ds_write2_b32 v137, v42, v106 offset0:200 offset1:232
	v_add_u32_e32 v138, 0x6800, v132
	ds_write2_b32 v139, v44, v108 offset0:96 offset1:128
	v_add_u32_e32 v139, 0x7400, v132
	ds_write2_b32 v140, v46, v110 offset0:104 offset1:136
	v_add_u32_e32 v140, 0x7800, v132
	ds_write2_b32 v138, v43, v107 offset0:76 offset1:108
	ds_write2_b32 v139, v45, v109 offset0:100 offset1:132
	ds_write2_b32 v140, v47, v111 offset0:108 offset1:140
	ds_write2_b32 v128, v80, v112 offset0:192 offset1:224
	ds_write2_b32 v133, v81, v113 offset0:68 offset1:100
	ds_write2_b32 v133, v82, v114 offset0:200 offset1:232
	ds_write2_b32 v134, v83, v115 offset0:76 offset1:108
	v_add_u32_e32 v128, 0x5200, v132
	ds_write2_b32 v128, v84, v116 offset0:96 offset1:128
	ds_write2_b32 v135, v85, v117 offset0:100 offset1:132
	v_add_u32_e32 v128, 0x5600, v132
	ds_write2_b32 v128, v86, v118 offset0:104 offset1:136
	ds_write2_b32 v136, v87, v119 offset0:108 offset1:140
	ds_write2_b32 v137, v88, v120 offset1:32
	ds_write2_b32 v137, v89, v121 offset0:132 offset1:164
	ds_write2_b32 v138, v90, v122 offset0:8 offset1:40
	ds_write2_b32 v138, v91, v123 offset0:140 offset1:172
	ds_write2_b32 v139, v92, v124 offset0:32 offset1:64
	ds_write2_b32 v139, v93, v125 offset0:164 offset1:196
	ds_write2_b32 v140, v94, v126 offset0:40 offset1:72
	ds_write2_b32 v140, v95, v127 offset0:172 offset1:204
